# operand-reuse k-snake MFMA order plus scalar-base LDS-DMA addressing
# speedup vs baseline: 1.0105x; 1.0046x over previous
.LBB0_169:
	s_add_u32 s34, s50, 0xfff80080
	s_addc_u32 s35, s51, -1
	s_add_i32 s52, 0, 0x10000
	s_cmp_eq_u32 s77, 28
	s_cselect_b32 s55, s36, s35
	s_cselect_b32 s54, s37, s34
	v_add_u32_e32 v145, s52, v142
	s_cselect_b32 s35, s41, s76
	s_cselect_b32 s34, s43, s71
	s_add_i32 s53, 0, 0x14000
	ds_read_b128 v[146:149], v145
	ds_read_b128 v[150:153], v145 offset:1024
	ds_read_b128 v[172:175], v145 offset:2048
	ds_read_b128 v[176:179], v145 offset:3072
	v_add_u32_e32 v145, s53, v142
	ds_read_b128 v[180:183], v145
	ds_read_b128 v[184:187], v145 offset:1024
	ds_read_b128 v[188:191], v145 offset:2048
	ds_read_b128 v[192:195], v145 offset:3072
	s_add_i32 m0, s57, 0xc000
	ds_read_b128 v[196:199], v144
	ds_read_b128 v[200:203], v144 offset:1024
	ds_read_b128 v[204:207], v144 offset:2048
	ds_read_b128 v[208:211], v144 offset:3072
	ds_read_b128 v[212:215], v144 offset:4096
	ds_read_b128 v[216:219], v144 offset:5120
	ds_read_b128 v[228:231], v144 offset:6144
	ds_read_b128 v[232:235], v144 offset:7168
	global_load_lds_dwordx4 v138, s[50:51]
	s_add_i32 m0, s57, 0xe000
	s_nop 0
	global_load_lds_dwordx4 v140, s[50:51]
	s_waitcnt vmcnt(8)
	s_waitcnt lgkmcnt(0)
	s_barrier
	s_setprio 1
	v_mfma_f32_16x16x32_bf16 v[128:131], v[146:149], v[196:199], v[128:131]
	v_mfma_f32_16x16x32_bf16 v[128:131], v[150:153], v[200:203], v[128:131]
	v_mfma_f32_16x16x32_bf16 v[124:127], v[176:179], v[200:203], v[124:127]
	v_mfma_f32_16x16x32_bf16 v[124:127], v[172:175], v[196:199], v[124:127]
	v_mfma_f32_16x16x32_bf16 v[108:111], v[172:175], v[204:207], v[108:111]
	v_mfma_f32_16x16x32_bf16 v[108:111], v[176:179], v[208:211], v[108:111]
	v_mfma_f32_16x16x32_bf16 v[112:115], v[150:153], v[208:211], v[112:115]
	v_mfma_f32_16x16x32_bf16 v[112:115], v[146:149], v[204:207], v[112:115]
	v_mfma_f32_16x16x32_bf16 v[96:99], v[146:149], v[212:215], v[96:99]
	v_mfma_f32_16x16x32_bf16 v[96:99], v[150:153], v[216:219], v[96:99]
	v_mfma_f32_16x16x32_bf16 v[92:95], v[176:179], v[216:219], v[92:95]
	v_mfma_f32_16x16x32_bf16 v[92:95], v[172:175], v[212:215], v[92:95]
	v_mfma_f32_16x16x32_bf16 v[76:79], v[172:175], v[228:231], v[76:79]
	v_mfma_f32_16x16x32_bf16 v[76:79], v[176:179], v[232:235], v[76:79]
	v_mfma_f32_16x16x32_bf16 v[80:83], v[150:153], v[232:235], v[80:83]
	v_mfma_f32_16x16x32_bf16 v[80:83], v[146:149], v[228:231], v[80:83]
	v_mfma_f32_16x16x32_bf16 v[120:123], v[180:183], v[196:199], v[120:123]
	v_mfma_f32_16x16x32_bf16 v[120:123], v[184:187], v[200:203], v[120:123]
	v_mfma_f32_16x16x32_bf16 v[116:119], v[192:195], v[200:203], v[116:119]
	v_mfma_f32_16x16x32_bf16 v[116:119], v[188:191], v[196:199], v[116:119]
	v_mfma_f32_16x16x32_bf16 v[100:103], v[188:191], v[204:207], v[100:103]
	v_mfma_f32_16x16x32_bf16 v[100:103], v[192:195], v[208:211], v[100:103]
	v_mfma_f32_16x16x32_bf16 v[104:107], v[184:187], v[208:211], v[104:107]
	v_mfma_f32_16x16x32_bf16 v[104:107], v[180:183], v[204:207], v[104:107]
	v_mfma_f32_16x16x32_bf16 v[88:91], v[180:183], v[212:215], v[88:91]
	v_mfma_f32_16x16x32_bf16 v[88:91], v[184:187], v[216:219], v[88:91]
	v_mfma_f32_16x16x32_bf16 v[84:87], v[192:195], v[216:219], v[84:87]
	v_mfma_f32_16x16x32_bf16 v[84:87], v[188:191], v[212:215], v[84:87]
	v_mfma_f32_16x16x32_bf16 v[68:71], v[188:191], v[228:231], v[68:71]
	v_mfma_f32_16x16x32_bf16 v[68:71], v[192:195], v[232:235], v[68:71]
	v_mfma_f32_16x16x32_bf16 v[72:75], v[184:187], v[232:235], v[72:75]
	v_mfma_f32_16x16x32_bf16 v[72:75], v[180:183], v[228:231], v[72:75]
	s_setprio 0
	s_barrier
	s_add_u32 s100, s54, s14
	s_addc_u32 s101, s55, s15
	s_add_i32 s52, s52, s19
	s_mov_b32 m0, s52
	ds_read_b128 v[196:199], v144 offset:16384
	ds_read_b128 v[200:203], v144 offset:17408
	ds_read_b128 v[204:207], v144 offset:18432
	ds_read_b128 v[208:211], v144 offset:19456
	ds_read_b128 v[212:215], v144 offset:20480
	ds_read_b128 v[216:219], v144 offset:21504
	ds_read_b128 v[228:231], v144 offset:22528
	ds_read_b128 v[232:235], v144 offset:23552
	global_load_lds_dwordx4 v134, s[34:35]
	s_add_i32 m0, s52, 0x2000
	s_add_u32 s96, s34, 0x4000
	s_addc_u32 s97, s35, 0
	s_add_i32 s52, s53, s19
	global_load_lds_dwordx4 v0, s[34:35]
	s_mov_b32 m0, s52
	s_nop 0
	global_load_lds_dwordx4 v134, s[96:97]
	s_add_i32 m0, s52, 0x2000
	s_nop 0
	global_load_lds_dwordx4 v0, s[96:97]
	s_mov_b32 m0, s57
	s_nop 0
	global_load_lds_dwordx4 v136, s[54:55]
	s_mov_b32 m0, s58
	s_nop 0
	global_load_lds_dwordx4 v132, s[54:55]
	s_waitcnt vmcnt(8)
	s_waitcnt lgkmcnt(0)
	s_barrier
	s_setprio 1
	v_mfma_f32_16x16x32_bf16 v[64:67], v[146:149], v[196:199], v[64:67]
	v_mfma_f32_16x16x32_bf16 v[64:67], v[150:153], v[200:203], v[64:67]
	v_mfma_f32_16x16x32_bf16 v[60:63], v[176:179], v[200:203], v[60:63]
	v_mfma_f32_16x16x32_bf16 v[60:63], v[172:175], v[196:199], v[60:63]
	v_mfma_f32_16x16x32_bf16 v[44:47], v[172:175], v[204:207], v[44:47]
	v_mfma_f32_16x16x32_bf16 v[44:47], v[176:179], v[208:211], v[44:47]
	v_mfma_f32_16x16x32_bf16 v[48:51], v[150:153], v[208:211], v[48:51]
	v_mfma_f32_16x16x32_bf16 v[48:51], v[146:149], v[204:207], v[48:51]
	v_mfma_f32_16x16x32_bf16 v[32:35], v[146:149], v[212:215], v[32:35]
	v_mfma_f32_16x16x32_bf16 v[32:35], v[150:153], v[216:219], v[32:35]
	v_mfma_f32_16x16x32_bf16 v[28:31], v[176:179], v[216:219], v[28:31]
	v_mfma_f32_16x16x32_bf16 v[28:31], v[172:175], v[212:215], v[28:31]
	v_mfma_f32_16x16x32_bf16 v[12:15], v[172:175], v[228:231], v[12:15]
	v_mfma_f32_16x16x32_bf16 v[12:15], v[176:179], v[232:235], v[12:15]
	v_mfma_f32_16x16x32_bf16 v[16:19], v[150:153], v[232:235], v[16:19]
	v_mfma_f32_16x16x32_bf16 v[16:19], v[146:149], v[228:231], v[16:19]
	v_mfma_f32_16x16x32_bf16 v[56:59], v[180:183], v[196:199], v[56:59]
	v_mfma_f32_16x16x32_bf16 v[56:59], v[184:187], v[200:203], v[56:59]
	v_mfma_f32_16x16x32_bf16 v[52:55], v[192:195], v[200:203], v[52:55]
	v_mfma_f32_16x16x32_bf16 v[52:55], v[188:191], v[196:199], v[52:55]
	v_mfma_f32_16x16x32_bf16 v[36:39], v[188:191], v[204:207], v[36:39]
	v_mfma_f32_16x16x32_bf16 v[36:39], v[192:195], v[208:211], v[36:39]
	v_mfma_f32_16x16x32_bf16 v[40:43], v[184:187], v[208:211], v[40:43]
	v_mfma_f32_16x16x32_bf16 v[40:43], v[180:183], v[204:207], v[40:43]
	v_mfma_f32_16x16x32_bf16 v[24:27], v[180:183], v[212:215], v[24:27]
	v_mfma_f32_16x16x32_bf16 v[24:27], v[184:187], v[216:219], v[24:27]
	v_mfma_f32_16x16x32_bf16 v[20:23], v[192:195], v[216:219], v[20:23]
	v_mfma_f32_16x16x32_bf16 v[20:23], v[188:191], v[212:215], v[20:23]
	v_mfma_f32_16x16x32_bf16 v[4:7], v[188:191], v[228:231], v[4:7]
	v_mfma_f32_16x16x32_bf16 v[4:7], v[192:195], v[232:235], v[4:7]
	v_mfma_f32_16x16x32_bf16 v[8:11], v[184:187], v[232:235], v[8:11]
	v_mfma_f32_16x16x32_bf16 v[8:11], v[180:183], v[228:231], v[8:11]
	s_setprio 0
	s_barrier
	s_add_i32 s52, 0, 0x18000
	v_add_u32_e32 v145, s52, v142
	s_add_i32 s53, 0, 0x1c000
	ds_read_b128 v[146:149], v145
	ds_read_b128 v[150:153], v145 offset:1024
	ds_read_b128 v[172:175], v145 offset:2048
	ds_read_b128 v[176:179], v145 offset:3072
	v_add_u32_e32 v145, s53, v142
	ds_read_b128 v[180:183], v145
	ds_read_b128 v[184:187], v145 offset:1024
	ds_read_b128 v[188:191], v145 offset:2048
	ds_read_b128 v[192:195], v145 offset:3072
	s_add_u32 s54, s54, 0x80000
	s_addc_u32 s55, s55, 0
	s_mov_b32 m0, s59
	ds_read_b128 v[196:199], v144 offset:32768
	ds_read_b128 v[200:203], v144 offset:33792
	ds_read_b128 v[204:207], v144 offset:34816
	ds_read_b128 v[208:211], v144 offset:35840
	ds_read_b128 v[212:215], v144 offset:36864
	ds_read_b128 v[216:219], v144 offset:37888
	ds_read_b128 v[228:231], v144 offset:38912
	ds_read_b128 v[232:235], v144 offset:39936
	global_load_lds_dwordx4 v136, s[54:55]
	s_mov_b32 m0, s60
	s_nop 0
	global_load_lds_dwordx4 v132, s[54:55]
	s_waitcnt vmcnt(8)
	s_waitcnt lgkmcnt(0)
	s_barrier
	s_setprio 1
	v_mfma_f32_16x16x32_bf16 v[128:131], v[146:149], v[196:199], v[128:131]
	v_mfma_f32_16x16x32_bf16 v[128:131], v[150:153], v[200:203], v[128:131]
	v_mfma_f32_16x16x32_bf16 v[124:127], v[176:179], v[200:203], v[124:127]
	v_mfma_f32_16x16x32_bf16 v[124:127], v[172:175], v[196:199], v[124:127]
	v_mfma_f32_16x16x32_bf16 v[108:111], v[172:175], v[204:207], v[108:111]
	v_mfma_f32_16x16x32_bf16 v[108:111], v[176:179], v[208:211], v[108:111]
	v_mfma_f32_16x16x32_bf16 v[112:115], v[150:153], v[208:211], v[112:115]
	v_mfma_f32_16x16x32_bf16 v[112:115], v[146:149], v[204:207], v[112:115]
	v_mfma_f32_16x16x32_bf16 v[96:99], v[146:149], v[212:215], v[96:99]
	v_mfma_f32_16x16x32_bf16 v[96:99], v[150:153], v[216:219], v[96:99]
	v_mfma_f32_16x16x32_bf16 v[92:95], v[176:179], v[216:219], v[92:95]
	v_mfma_f32_16x16x32_bf16 v[92:95], v[172:175], v[212:215], v[92:95]
	v_mfma_f32_16x16x32_bf16 v[76:79], v[172:175], v[228:231], v[76:79]
	v_mfma_f32_16x16x32_bf16 v[76:79], v[176:179], v[232:235], v[76:79]
	v_mfma_f32_16x16x32_bf16 v[80:83], v[150:153], v[232:235], v[80:83]
	v_mfma_f32_16x16x32_bf16 v[80:83], v[146:149], v[228:231], v[80:83]
	v_mfma_f32_16x16x32_bf16 v[120:123], v[180:183], v[196:199], v[120:123]
	v_mfma_f32_16x16x32_bf16 v[120:123], v[184:187], v[200:203], v[120:123]
	v_mfma_f32_16x16x32_bf16 v[116:119], v[192:195], v[200:203], v[116:119]
	v_mfma_f32_16x16x32_bf16 v[116:119], v[188:191], v[196:199], v[116:119]
	v_mfma_f32_16x16x32_bf16 v[100:103], v[188:191], v[204:207], v[100:103]
	v_mfma_f32_16x16x32_bf16 v[100:103], v[192:195], v[208:211], v[100:103]
	v_mfma_f32_16x16x32_bf16 v[104:107], v[184:187], v[208:211], v[104:107]
	v_mfma_f32_16x16x32_bf16 v[104:107], v[180:183], v[204:207], v[104:107]
	v_mfma_f32_16x16x32_bf16 v[88:91], v[180:183], v[212:215], v[88:91]
	v_mfma_f32_16x16x32_bf16 v[88:91], v[184:187], v[216:219], v[88:91]
	v_mfma_f32_16x16x32_bf16 v[84:87], v[192:195], v[216:219], v[84:87]
	v_mfma_f32_16x16x32_bf16 v[84:87], v[188:191], v[212:215], v[84:87]
	v_mfma_f32_16x16x32_bf16 v[68:71], v[188:191], v[228:231], v[68:71]
	v_mfma_f32_16x16x32_bf16 v[68:71], v[192:195], v[232:235], v[68:71]
	v_mfma_f32_16x16x32_bf16 v[72:75], v[184:187], v[232:235], v[72:75]
	v_mfma_f32_16x16x32_bf16 v[72:75], v[180:183], v[228:231], v[72:75]
	s_setprio 0
	s_barrier
	s_add_u32 s54, s34, 0x160000
	s_addc_u32 s55, s35, 0
	s_add_i32 s52, s52, s19
	s_mov_b32 m0, s52
	ds_read_b128 v[196:199], v144 offset:49152
	ds_read_b128 v[200:203], v144 offset:50176
	ds_read_b128 v[204:207], v144 offset:51200
	ds_read_b128 v[208:211], v144 offset:52224
	ds_read_b128 v[212:215], v144 offset:53248
	ds_read_b128 v[216:219], v144 offset:54272
	ds_read_b128 v[228:231], v144 offset:55296
	ds_read_b128 v[232:235], v144 offset:56320
	global_load_lds_dwordx4 v134, s[54:55]
	s_add_i32 m0, s52, 0x2000
	s_add_u32 s34, s34, 0x164000
	s_addc_u32 s35, s35, 0
	s_add_i32 s52, s53, s19
	global_load_lds_dwordx4 v0, s[54:55]
	s_mov_b32 m0, s52
	s_nop 0
	global_load_lds_dwordx4 v134, s[34:35]
	s_add_i32 m0, s52, 0x2000
	s_nop 0
	global_load_lds_dwordx4 v0, s[34:35]
	s_mov_b32 m0, s61
	s_nop 0
	global_load_lds_dwordx4 v136, s[100:101]
	s_mov_b32 m0, s62
	s_nop 0
	global_load_lds_dwordx4 v132, s[100:101]
	s_waitcnt vmcnt(8)
	s_waitcnt lgkmcnt(0)
	s_barrier
	s_setprio 1
	v_mfma_f32_16x16x32_bf16 v[64:67], v[146:149], v[196:199], v[64:67]
	v_mfma_f32_16x16x32_bf16 v[64:67], v[150:153], v[200:203], v[64:67]
	v_mfma_f32_16x16x32_bf16 v[60:63], v[176:179], v[200:203], v[60:63]
	v_mfma_f32_16x16x32_bf16 v[60:63], v[172:175], v[196:199], v[60:63]
	v_mfma_f32_16x16x32_bf16 v[44:47], v[172:175], v[204:207], v[44:47]
	v_mfma_f32_16x16x32_bf16 v[44:47], v[176:179], v[208:211], v[44:47]
	v_mfma_f32_16x16x32_bf16 v[48:51], v[150:153], v[208:211], v[48:51]
	v_mfma_f32_16x16x32_bf16 v[48:51], v[146:149], v[204:207], v[48:51]
	v_mfma_f32_16x16x32_bf16 v[32:35], v[146:149], v[212:215], v[32:35]
	v_mfma_f32_16x16x32_bf16 v[32:35], v[150:153], v[216:219], v[32:35]
	v_mfma_f32_16x16x32_bf16 v[28:31], v[176:179], v[216:219], v[28:31]
	v_mfma_f32_16x16x32_bf16 v[28:31], v[172:175], v[212:215], v[28:31]
	v_mfma_f32_16x16x32_bf16 v[12:15], v[172:175], v[228:231], v[12:15]
	v_mfma_f32_16x16x32_bf16 v[12:15], v[176:179], v[232:235], v[12:15]
	v_mfma_f32_16x16x32_bf16 v[16:19], v[150:153], v[232:235], v[16:19]
	v_mfma_f32_16x16x32_bf16 v[16:19], v[146:149], v[228:231], v[16:19]
	v_mfma_f32_16x16x32_bf16 v[56:59], v[180:183], v[196:199], v[56:59]
	v_mfma_f32_16x16x32_bf16 v[56:59], v[184:187], v[200:203], v[56:59]
	v_mfma_f32_16x16x32_bf16 v[52:55], v[192:195], v[200:203], v[52:55]
	v_mfma_f32_16x16x32_bf16 v[52:55], v[188:191], v[196:199], v[52:55]
	v_mfma_f32_16x16x32_bf16 v[36:39], v[188:191], v[204:207], v[36:39]
	v_mfma_f32_16x16x32_bf16 v[36:39], v[192:195], v[208:211], v[36:39]
	v_mfma_f32_16x16x32_bf16 v[40:43], v[184:187], v[208:211], v[40:43]
	v_mfma_f32_16x16x32_bf16 v[40:43], v[180:183], v[204:207], v[40:43]
	v_mfma_f32_16x16x32_bf16 v[24:27], v[180:183], v[212:215], v[24:27]
	v_mfma_f32_16x16x32_bf16 v[24:27], v[184:187], v[216:219], v[24:27]
	v_mfma_f32_16x16x32_bf16 v[20:23], v[192:195], v[216:219], v[20:23]
	v_mfma_f32_16x16x32_bf16 v[20:23], v[188:191], v[212:215], v[20:23]
	v_mfma_f32_16x16x32_bf16 v[4:7], v[188:191], v[228:231], v[4:7]
	v_mfma_f32_16x16x32_bf16 v[4:7], v[192:195], v[232:235], v[4:7]
	v_mfma_f32_16x16x32_bf16 v[8:11], v[184:187], v[232:235], v[8:11]
	v_mfma_f32_16x16x32_bf16 v[8:11], v[180:183], v[228:231], v[8:11]
	s_setprio 0
	s_barrier
	s_add_i32 s77, s77, 2
	s_add_u32 s71, s71, 0x2c0000
	s_addc_u32 s76, s76, 0
	s_add_u32 s50, s50, 0x100
	s_addc_u32 s51, s51, 0
	s_cmp_gt_u32 s77, 29
	s_cbranch_scc0 .LBB0_169
	s_and_b64 vcc, exec, s[28:29]
	s_cbranch_vccz .LBB0_172
	s_barrier

.LBB0_243:
	s_add_u32 s34, s44, 0xfff80080
	s_addc_u32 s35, s45, -1
	s_add_i32 s52, 0, 0x10000
	s_cmp_eq_u32 vcc_hi, 28
	s_cselect_b32 s47, s36, s35
	s_cselect_b32 s46, s37, s34
	s_cselect_b32 s35, s55, vcc_lo
	s_cselect_b32 s34, s57, s63
	s_add_i32 s68, 0, 0x14000
	v_add_u32_e32 v144, s52, v155
	v_add_u32_e32 v180, s68, v155
	ds_read_b128 v[132:135], v144
	ds_read_b128 v[136:139], v144 offset:1024
	ds_read_b128 v[140:143], v144 offset:2048
	ds_read_b128 v[144:147], v144 offset:3072
	ds_read_b128 v[176:179], v180
	ds_read_b128 v[182:185], v180 offset:1024
	ds_read_b128 v[186:189], v180 offset:2048
	ds_read_b128 v[190:193], v180 offset:3072
	s_add_i32 m0, s69, 0xc000
	ds_read_b128 v[194:197], v181
	ds_read_b128 v[198:201], v181 offset:1024
	ds_read_b128 v[202:205], v181 offset:2048
	ds_read_b128 v[206:209], v181 offset:3072
	ds_read_b128 v[210:213], v181 offset:4096
	ds_read_b128 v[214:217], v181 offset:5120
	ds_read_b128 v[228:231], v181 offset:6144
	ds_read_b128 v[232:235], v181 offset:7168
	global_load_lds_dwordx4 v172, s[44:45]
	s_add_i32 m0, s69, 0xe000
	s_nop 0
	global_load_lds_dwordx4 v174, s[44:45]
	s_waitcnt vmcnt(8)
	s_waitcnt lgkmcnt(0)
	s_barrier
	s_setprio 1
	v_mfma_f32_16x16x32_bf16 v[128:131], v[132:135], v[194:197], v[128:131]
	v_mfma_f32_16x16x32_bf16 v[128:131], v[136:139], v[198:201], v[128:131]
	v_mfma_f32_16x16x32_bf16 v[124:127], v[144:147], v[198:201], v[124:127]
	v_mfma_f32_16x16x32_bf16 v[124:127], v[140:143], v[194:197], v[124:127]
	v_mfma_f32_16x16x32_bf16 v[108:111], v[140:143], v[202:205], v[108:111]
	v_mfma_f32_16x16x32_bf16 v[108:111], v[144:147], v[206:209], v[108:111]
	v_mfma_f32_16x16x32_bf16 v[112:115], v[136:139], v[206:209], v[112:115]
	v_mfma_f32_16x16x32_bf16 v[112:115], v[132:135], v[202:205], v[112:115]
	v_mfma_f32_16x16x32_bf16 v[96:99], v[132:135], v[210:213], v[96:99]
	v_mfma_f32_16x16x32_bf16 v[96:99], v[136:139], v[214:217], v[96:99]
	v_mfma_f32_16x16x32_bf16 v[92:95], v[144:147], v[214:217], v[92:95]
	v_mfma_f32_16x16x32_bf16 v[92:95], v[140:143], v[210:213], v[92:95]
	v_mfma_f32_16x16x32_bf16 v[76:79], v[140:143], v[228:231], v[76:79]
	v_mfma_f32_16x16x32_bf16 v[76:79], v[144:147], v[232:235], v[76:79]
	v_mfma_f32_16x16x32_bf16 v[80:83], v[136:139], v[232:235], v[80:83]
	v_mfma_f32_16x16x32_bf16 v[80:83], v[132:135], v[228:231], v[80:83]
	v_mfma_f32_16x16x32_bf16 v[120:123], v[176:179], v[194:197], v[120:123]
	v_mfma_f32_16x16x32_bf16 v[120:123], v[182:185], v[198:201], v[120:123]
	v_mfma_f32_16x16x32_bf16 v[116:119], v[190:193], v[198:201], v[116:119]
	v_mfma_f32_16x16x32_bf16 v[116:119], v[186:189], v[194:197], v[116:119]
	v_mfma_f32_16x16x32_bf16 v[100:103], v[186:189], v[202:205], v[100:103]
	v_mfma_f32_16x16x32_bf16 v[100:103], v[190:193], v[206:209], v[100:103]
	v_mfma_f32_16x16x32_bf16 v[104:107], v[182:185], v[206:209], v[104:107]
	v_mfma_f32_16x16x32_bf16 v[104:107], v[176:179], v[202:205], v[104:107]
	v_mfma_f32_16x16x32_bf16 v[88:91], v[176:179], v[210:213], v[88:91]
	v_mfma_f32_16x16x32_bf16 v[88:91], v[182:185], v[214:217], v[88:91]
	v_mfma_f32_16x16x32_bf16 v[84:87], v[190:193], v[214:217], v[84:87]
	v_mfma_f32_16x16x32_bf16 v[84:87], v[186:189], v[210:213], v[84:87]
	v_mfma_f32_16x16x32_bf16 v[68:71], v[186:189], v[228:231], v[68:71]
	v_mfma_f32_16x16x32_bf16 v[68:71], v[190:193], v[232:235], v[68:71]
	v_mfma_f32_16x16x32_bf16 v[72:75], v[182:185], v[232:235], v[72:75]
	v_mfma_f32_16x16x32_bf16 v[72:75], v[176:179], v[228:231], v[72:75]
	s_setprio 0
	s_barrier
	s_add_u32 s100, s46, s14
	s_addc_u32 s101, s47, s15
	s_add_i32 s52, s52, s2
	s_mov_b32 m0, s52
	ds_read_b128 v[194:197], v181 offset:16384
	ds_read_b128 v[198:201], v181 offset:17408
	ds_read_b128 v[202:205], v181 offset:18432
	ds_read_b128 v[206:209], v181 offset:19456
	ds_read_b128 v[210:213], v181 offset:20480
	ds_read_b128 v[214:217], v181 offset:21504
	ds_read_b128 v[228:231], v181 offset:22528
	ds_read_b128 v[232:235], v181 offset:23552
	global_load_lds_dwordx4 v150, s[34:35]
	s_add_i32 m0, s52, 0x2000
	s_add_u32 s52, s34, 0x4000
	s_addc_u32 s53, s35, 0
	s_add_i32 s68, s68, s2
	global_load_lds_dwordx4 v0, s[34:35]
	s_mov_b32 m0, s68
	s_nop 0
	global_load_lds_dwordx4 v150, s[52:53]
	s_add_i32 m0, s68, 0x2000
	s_nop 0
	global_load_lds_dwordx4 v0, s[52:53]
	s_mov_b32 m0, s69
	s_nop 0
	global_load_lds_dwordx4 v152, s[46:47]
	s_mov_b32 m0, s71
	s_nop 0
	global_load_lds_dwordx4 v148, s[46:47]
	s_waitcnt vmcnt(8)
	s_waitcnt lgkmcnt(0)
	s_barrier
	s_setprio 1
	v_mfma_f32_16x16x32_bf16 v[64:67], v[132:135], v[194:197], v[64:67]
	v_mfma_f32_16x16x32_bf16 v[64:67], v[136:139], v[198:201], v[64:67]
	v_mfma_f32_16x16x32_bf16 v[60:63], v[144:147], v[198:201], v[60:63]
	v_mfma_f32_16x16x32_bf16 v[60:63], v[140:143], v[194:197], v[60:63]
	v_mfma_f32_16x16x32_bf16 v[44:47], v[140:143], v[202:205], v[44:47]
	v_mfma_f32_16x16x32_bf16 v[44:47], v[144:147], v[206:209], v[44:47]
	v_mfma_f32_16x16x32_bf16 v[48:51], v[136:139], v[206:209], v[48:51]
	v_mfma_f32_16x16x32_bf16 v[48:51], v[132:135], v[202:205], v[48:51]
	v_mfma_f32_16x16x32_bf16 v[32:35], v[132:135], v[210:213], v[32:35]
	v_mfma_f32_16x16x32_bf16 v[32:35], v[136:139], v[214:217], v[32:35]
	v_mfma_f32_16x16x32_bf16 v[28:31], v[144:147], v[214:217], v[28:31]
	v_mfma_f32_16x16x32_bf16 v[28:31], v[140:143], v[210:213], v[28:31]
	v_mfma_f32_16x16x32_bf16 v[12:15], v[140:143], v[228:231], v[12:15]
	v_mfma_f32_16x16x32_bf16 v[12:15], v[144:147], v[232:235], v[12:15]
	v_mfma_f32_16x16x32_bf16 v[16:19], v[136:139], v[232:235], v[16:19]
	v_mfma_f32_16x16x32_bf16 v[16:19], v[132:135], v[228:231], v[16:19]
	v_mfma_f32_16x16x32_bf16 v[56:59], v[176:179], v[194:197], v[56:59]
	v_mfma_f32_16x16x32_bf16 v[56:59], v[182:185], v[198:201], v[56:59]
	v_mfma_f32_16x16x32_bf16 v[52:55], v[190:193], v[198:201], v[52:55]
	v_mfma_f32_16x16x32_bf16 v[52:55], v[186:189], v[194:197], v[52:55]
	v_mfma_f32_16x16x32_bf16 v[36:39], v[186:189], v[202:205], v[36:39]
	v_mfma_f32_16x16x32_bf16 v[36:39], v[190:193], v[206:209], v[36:39]
	v_mfma_f32_16x16x32_bf16 v[40:43], v[182:185], v[206:209], v[40:43]
	v_mfma_f32_16x16x32_bf16 v[40:43], v[176:179], v[202:205], v[40:43]
	v_mfma_f32_16x16x32_bf16 v[24:27], v[176:179], v[210:213], v[24:27]
	v_mfma_f32_16x16x32_bf16 v[24:27], v[182:185], v[214:217], v[24:27]
	v_mfma_f32_16x16x32_bf16 v[20:23], v[190:193], v[214:217], v[20:23]
	v_mfma_f32_16x16x32_bf16 v[20:23], v[186:189], v[210:213], v[20:23]
	v_mfma_f32_16x16x32_bf16 v[4:7], v[186:189], v[228:231], v[4:7]
	v_mfma_f32_16x16x32_bf16 v[4:7], v[190:193], v[232:235], v[4:7]
	v_mfma_f32_16x16x32_bf16 v[8:11], v[182:185], v[232:235], v[8:11]
	v_mfma_f32_16x16x32_bf16 v[8:11], v[176:179], v[228:231], v[8:11]
	s_setprio 0
	s_barrier
	s_add_i32 s52, 0, 0x18000
	s_add_i32 s53, 0, 0x1c000
	v_add_u32_e32 v144, s52, v155
	v_add_u32_e32 v180, s53, v155
	ds_read_b128 v[132:135], v144
	ds_read_b128 v[136:139], v144 offset:1024
	ds_read_b128 v[140:143], v144 offset:2048
	ds_read_b128 v[144:147], v144 offset:3072
	ds_read_b128 v[176:179], v180
	ds_read_b128 v[182:185], v180 offset:1024
	ds_read_b128 v[186:189], v180 offset:2048
	ds_read_b128 v[190:193], v180 offset:3072
	s_add_u32 s46, s46, 0x80000
	s_addc_u32 s47, s47, 0
	s_mov_b32 m0, s88
	ds_read_b128 v[194:197], v181 offset:32768
	ds_read_b128 v[198:201], v181 offset:33792
	ds_read_b128 v[202:205], v181 offset:34816
	ds_read_b128 v[206:209], v181 offset:35840
	ds_read_b128 v[210:213], v181 offset:36864
	ds_read_b128 v[214:217], v181 offset:37888
	ds_read_b128 v[228:231], v181 offset:38912
	ds_read_b128 v[232:235], v181 offset:39936
	global_load_lds_dwordx4 v152, s[46:47]
	s_mov_b32 m0, s96
	s_nop 0
	global_load_lds_dwordx4 v148, s[46:47]
	s_waitcnt vmcnt(8)
	s_waitcnt lgkmcnt(0)
	s_barrier
	s_setprio 1
	v_mfma_f32_16x16x32_bf16 v[128:131], v[132:135], v[194:197], v[128:131]
	v_mfma_f32_16x16x32_bf16 v[128:131], v[136:139], v[198:201], v[128:131]
	v_mfma_f32_16x16x32_bf16 v[124:127], v[144:147], v[198:201], v[124:127]
	v_mfma_f32_16x16x32_bf16 v[124:127], v[140:143], v[194:197], v[124:127]
	v_mfma_f32_16x16x32_bf16 v[108:111], v[140:143], v[202:205], v[108:111]
	v_mfma_f32_16x16x32_bf16 v[108:111], v[144:147], v[206:209], v[108:111]
	v_mfma_f32_16x16x32_bf16 v[112:115], v[136:139], v[206:209], v[112:115]
	v_mfma_f32_16x16x32_bf16 v[112:115], v[132:135], v[202:205], v[112:115]
	v_mfma_f32_16x16x32_bf16 v[96:99], v[132:135], v[210:213], v[96:99]
	v_mfma_f32_16x16x32_bf16 v[96:99], v[136:139], v[214:217], v[96:99]
	v_mfma_f32_16x16x32_bf16 v[92:95], v[144:147], v[214:217], v[92:95]
	v_mfma_f32_16x16x32_bf16 v[92:95], v[140:143], v[210:213], v[92:95]
	v_mfma_f32_16x16x32_bf16 v[76:79], v[140:143], v[228:231], v[76:79]
	v_mfma_f32_16x16x32_bf16 v[76:79], v[144:147], v[232:235], v[76:79]
	v_mfma_f32_16x16x32_bf16 v[80:83], v[136:139], v[232:235], v[80:83]
	v_mfma_f32_16x16x32_bf16 v[80:83], v[132:135], v[228:231], v[80:83]
	v_mfma_f32_16x16x32_bf16 v[120:123], v[176:179], v[194:197], v[120:123]
	v_mfma_f32_16x16x32_bf16 v[120:123], v[182:185], v[198:201], v[120:123]
	v_mfma_f32_16x16x32_bf16 v[116:119], v[190:193], v[198:201], v[116:119]
	v_mfma_f32_16x16x32_bf16 v[116:119], v[186:189], v[194:197], v[116:119]
	v_mfma_f32_16x16x32_bf16 v[100:103], v[186:189], v[202:205], v[100:103]
	v_mfma_f32_16x16x32_bf16 v[100:103], v[190:193], v[206:209], v[100:103]
	v_mfma_f32_16x16x32_bf16 v[104:107], v[182:185], v[206:209], v[104:107]
	v_mfma_f32_16x16x32_bf16 v[104:107], v[176:179], v[202:205], v[104:107]
	v_mfma_f32_16x16x32_bf16 v[88:91], v[176:179], v[210:213], v[88:91]
	v_mfma_f32_16x16x32_bf16 v[88:91], v[182:185], v[214:217], v[88:91]
	v_mfma_f32_16x16x32_bf16 v[84:87], v[190:193], v[214:217], v[84:87]
	v_mfma_f32_16x16x32_bf16 v[84:87], v[186:189], v[210:213], v[84:87]
	v_mfma_f32_16x16x32_bf16 v[68:71], v[186:189], v[228:231], v[68:71]
	v_mfma_f32_16x16x32_bf16 v[68:71], v[190:193], v[232:235], v[68:71]
	v_mfma_f32_16x16x32_bf16 v[72:75], v[182:185], v[232:235], v[72:75]
	v_mfma_f32_16x16x32_bf16 v[72:75], v[176:179], v[228:231], v[72:75]
	s_setprio 0
	s_barrier
	s_add_u32 s46, s34, 0x70000
	s_addc_u32 s47, s35, 0
	s_add_i32 s52, s52, s2
	s_mov_b32 m0, s52
	ds_read_b128 v[194:197], v181 offset:49152
	ds_read_b128 v[198:201], v181 offset:50176
	ds_read_b128 v[202:205], v181 offset:51200
	ds_read_b128 v[206:209], v181 offset:52224
	ds_read_b128 v[210:213], v181 offset:53248
	ds_read_b128 v[214:217], v181 offset:54272
	ds_read_b128 v[228:231], v181 offset:55296
	ds_read_b128 v[232:235], v181 offset:56320
	global_load_lds_dwordx4 v150, s[46:47]
	s_add_i32 m0, s52, 0x2000
	s_add_u32 s34, s34, 0x74000
	global_load_lds_dwordx4 v0, s[46:47]
	s_addc_u32 s35, s35, 0
	s_add_i32 s46, s53, s2
	s_mov_b32 m0, s46
	s_nop 0
	global_load_lds_dwordx4 v150, s[34:35]
	s_add_i32 m0, s46, 0x2000
	s_nop 0
	global_load_lds_dwordx4 v0, s[34:35]
	s_mov_b32 m0, s97
	s_nop 0
	global_load_lds_dwordx4 v152, s[100:101]
	s_mov_b32 m0, s76
	s_nop 0
	global_load_lds_dwordx4 v148, s[100:101]
	s_waitcnt vmcnt(8)
	s_waitcnt lgkmcnt(0)
	s_barrier
	s_setprio 1
	v_mfma_f32_16x16x32_bf16 v[64:67], v[132:135], v[194:197], v[64:67]
	v_mfma_f32_16x16x32_bf16 v[64:67], v[136:139], v[198:201], v[64:67]
	v_mfma_f32_16x16x32_bf16 v[60:63], v[144:147], v[198:201], v[60:63]
	v_mfma_f32_16x16x32_bf16 v[60:63], v[140:143], v[194:197], v[60:63]
	v_mfma_f32_16x16x32_bf16 v[44:47], v[140:143], v[202:205], v[44:47]
	v_mfma_f32_16x16x32_bf16 v[44:47], v[144:147], v[206:209], v[44:47]
	v_mfma_f32_16x16x32_bf16 v[48:51], v[136:139], v[206:209], v[48:51]
	v_mfma_f32_16x16x32_bf16 v[48:51], v[132:135], v[202:205], v[48:51]
	v_mfma_f32_16x16x32_bf16 v[32:35], v[132:135], v[210:213], v[32:35]
	v_mfma_f32_16x16x32_bf16 v[32:35], v[136:139], v[214:217], v[32:35]
	v_mfma_f32_16x16x32_bf16 v[28:31], v[144:147], v[214:217], v[28:31]
	v_mfma_f32_16x16x32_bf16 v[28:31], v[140:143], v[210:213], v[28:31]
	v_mfma_f32_16x16x32_bf16 v[12:15], v[140:143], v[228:231], v[12:15]
	v_mfma_f32_16x16x32_bf16 v[12:15], v[144:147], v[232:235], v[12:15]
	v_mfma_f32_16x16x32_bf16 v[16:19], v[136:139], v[232:235], v[16:19]
	v_mfma_f32_16x16x32_bf16 v[16:19], v[132:135], v[228:231], v[16:19]
	v_mfma_f32_16x16x32_bf16 v[56:59], v[176:179], v[194:197], v[56:59]
	v_mfma_f32_16x16x32_bf16 v[56:59], v[182:185], v[198:201], v[56:59]
	v_mfma_f32_16x16x32_bf16 v[52:55], v[190:193], v[198:201], v[52:55]
	v_mfma_f32_16x16x32_bf16 v[52:55], v[186:189], v[194:197], v[52:55]
	v_mfma_f32_16x16x32_bf16 v[36:39], v[186:189], v[202:205], v[36:39]
	v_mfma_f32_16x16x32_bf16 v[36:39], v[190:193], v[206:209], v[36:39]
	v_mfma_f32_16x16x32_bf16 v[40:43], v[182:185], v[206:209], v[40:43]
	v_mfma_f32_16x16x32_bf16 v[40:43], v[176:179], v[202:205], v[40:43]
	v_mfma_f32_16x16x32_bf16 v[24:27], v[176:179], v[210:213], v[24:27]
	v_mfma_f32_16x16x32_bf16 v[24:27], v[182:185], v[214:217], v[24:27]
	v_mfma_f32_16x16x32_bf16 v[20:23], v[190:193], v[214:217], v[20:23]
	v_mfma_f32_16x16x32_bf16 v[20:23], v[186:189], v[210:213], v[20:23]
	v_mfma_f32_16x16x32_bf16 v[4:7], v[186:189], v[228:231], v[4:7]
	v_mfma_f32_16x16x32_bf16 v[4:7], v[190:193], v[232:235], v[4:7]
	v_mfma_f32_16x16x32_bf16 v[8:11], v[182:185], v[232:235], v[8:11]
	v_mfma_f32_16x16x32_bf16 v[8:11], v[176:179], v[228:231], v[8:11]
	s_setprio 0
	s_barrier
	s_add_i32 vcc_hi, vcc_hi, 2
	s_add_u32 s63, s63, 0xe0000
	s_addc_u32 vcc_lo, vcc_lo, 0
	s_add_u32 s44, s44, 0x100
	s_addc_u32 s45, s45, 0
	s_cmp_gt_u32 vcc_hi, 29
	s_cbranch_scc0 .LBB0_243
	s_and_b64 vcc, exec, s[28:29]
	s_cbranch_vccz .LBB0_246
	s_barrier

.LBB0_559:
	s_add_i32 vcc_lo, s34, 2
	s_add_u32 s35, s42, 0x80
	s_addc_u32 s52, s43, 0
	s_add_i32 s53, 0, 0x10000
	s_cmp_eq_u32 s77, s34
	s_cselect_b32 s57, s51, s52
	s_cselect_b32 s56, s50, s35
	s_cselect_b32 s35, s36, s97
	s_cselect_b32 s34, s37, s49
	s_add_i32 s68, 0, 0x14000
	v_add_u32_e32 v136, s53, v200
	v_add_u32_e32 v186, s68, v200
	ds_read_b128 v[116:119], v136
	ds_read_b128 v[120:123], v136 offset:1024
	ds_read_b128 v[124:127], v136 offset:2048
	ds_read_b128 v[136:139], v136 offset:3072
	ds_read_b128 v[148:151], v186
	ds_read_b128 v[152:155], v186 offset:1024
	ds_read_b128 v[182:185], v186 offset:2048
	ds_read_b128 v[186:189], v186 offset:3072
	s_add_i32 m0, s59, 0xc000
	ds_read_b128 v[190:193], v202
	ds_read_b128 v[194:197], v202 offset:1024
	ds_read_b128 v[204:207], v202 offset:2048
	ds_read_b128 v[208:211], v202 offset:3072
	ds_read_b128 v[212:215], v202 offset:4096
	ds_read_b128 v[216:219], v202 offset:5120
	ds_read_b128 v[228:231], v202 offset:6144
	ds_read_b128 v[232:235], v202 offset:7168
	global_load_lds_dwordx4 v178, s[42:43]
	s_add_i32 m0, s59, 0xe000
	s_nop 0
	global_load_lds_dwordx4 v180, s[42:43]
	s_waitcnt vmcnt(8)
	s_waitcnt lgkmcnt(0)
	s_barrier
	s_setprio 1
	v_mfma_f32_16x16x32_bf16 v[144:147], v[116:119], v[190:193], v[144:147]
	v_mfma_f32_16x16x32_bf16 v[144:147], v[120:123], v[194:197], v[144:147]
	v_mfma_f32_16x16x32_bf16 v[140:143], v[136:139], v[194:197], v[140:143]
	v_mfma_f32_16x16x32_bf16 v[140:143], v[124:127], v[190:193], v[140:143]
	v_mfma_f32_16x16x32_bf16 v[108:111], v[124:127], v[204:207], v[108:111]
	v_mfma_f32_16x16x32_bf16 v[108:111], v[136:139], v[208:211], v[108:111]
	v_mfma_f32_16x16x32_bf16 v[112:115], v[120:123], v[208:211], v[112:115]
	v_mfma_f32_16x16x32_bf16 v[112:115], v[116:119], v[204:207], v[112:115]
	v_mfma_f32_16x16x32_bf16 v[96:99], v[116:119], v[212:215], v[96:99]
	v_mfma_f32_16x16x32_bf16 v[96:99], v[120:123], v[216:219], v[96:99]
	v_mfma_f32_16x16x32_bf16 v[92:95], v[136:139], v[216:219], v[92:95]
	v_mfma_f32_16x16x32_bf16 v[92:95], v[124:127], v[212:215], v[92:95]
	v_mfma_f32_16x16x32_bf16 v[76:79], v[124:127], v[228:231], v[76:79]
	v_mfma_f32_16x16x32_bf16 v[76:79], v[136:139], v[232:235], v[76:79]
	v_mfma_f32_16x16x32_bf16 v[80:83], v[120:123], v[232:235], v[80:83]
	v_mfma_f32_16x16x32_bf16 v[80:83], v[116:119], v[228:231], v[80:83]
	v_mfma_f32_16x16x32_bf16 v[132:135], v[148:151], v[190:193], v[132:135]
	v_mfma_f32_16x16x32_bf16 v[132:135], v[152:155], v[194:197], v[132:135]
	v_mfma_f32_16x16x32_bf16 v[128:131], v[186:189], v[194:197], v[128:131]
	v_mfma_f32_16x16x32_bf16 v[128:131], v[182:185], v[190:193], v[128:131]
	v_mfma_f32_16x16x32_bf16 v[100:103], v[182:185], v[204:207], v[100:103]
	v_mfma_f32_16x16x32_bf16 v[100:103], v[186:189], v[208:211], v[100:103]
	v_mfma_f32_16x16x32_bf16 v[104:107], v[152:155], v[208:211], v[104:107]
	v_mfma_f32_16x16x32_bf16 v[104:107], v[148:151], v[204:207], v[104:107]
	v_mfma_f32_16x16x32_bf16 v[88:91], v[148:151], v[212:215], v[88:91]
	v_mfma_f32_16x16x32_bf16 v[88:91], v[152:155], v[216:219], v[88:91]
	v_mfma_f32_16x16x32_bf16 v[84:87], v[186:189], v[216:219], v[84:87]
	v_mfma_f32_16x16x32_bf16 v[84:87], v[182:185], v[212:215], v[84:87]
	v_mfma_f32_16x16x32_bf16 v[68:71], v[182:185], v[228:231], v[68:71]
	v_mfma_f32_16x16x32_bf16 v[68:71], v[186:189], v[232:235], v[68:71]
	v_mfma_f32_16x16x32_bf16 v[72:75], v[152:155], v[232:235], v[72:75]
	v_mfma_f32_16x16x32_bf16 v[72:75], v[148:151], v[228:231], v[72:75]
	s_setprio 0
	s_barrier
	s_add_u32 s100, s56, s14
	s_addc_u32 s101, s57, s15
	s_add_i32 s52, s53, s58
	s_mov_b32 m0, s52
	ds_read_b128 v[190:193], v202 offset:16384
	ds_read_b128 v[194:197], v202 offset:17408
	ds_read_b128 v[204:207], v202 offset:18432
	ds_read_b128 v[208:211], v202 offset:19456
	ds_read_b128 v[212:215], v202 offset:20480
	ds_read_b128 v[216:219], v202 offset:21504
	ds_read_b128 v[228:231], v202 offset:22528
	ds_read_b128 v[232:235], v202 offset:23552
	global_load_lds_dwordx4 v174, s[34:35]
	s_add_i32 m0, s52, 0x2000
	s_add_u32 s52, s34, 0x4000
	s_addc_u32 s53, s35, 0
	s_add_i32 s68, s68, s58
	global_load_lds_dwordx4 v0, s[34:35]
	s_mov_b32 m0, s68
	s_nop 0
	global_load_lds_dwordx4 v174, s[52:53]
	s_add_i32 m0, s68, 0x2000
	s_nop 0
	global_load_lds_dwordx4 v0, s[52:53]
	s_mov_b32 m0, s59
	s_nop 0
	global_load_lds_dwordx4 v176, s[56:57]
	s_mov_b32 m0, s60
	s_nop 0
	global_load_lds_dwordx4 v172, s[56:57]
	s_waitcnt vmcnt(8)
	s_waitcnt lgkmcnt(0)
	s_barrier
	s_setprio 1
	v_mfma_f32_16x16x32_bf16 v[64:67], v[116:119], v[190:193], v[64:67]
	v_mfma_f32_16x16x32_bf16 v[64:67], v[120:123], v[194:197], v[64:67]
	v_mfma_f32_16x16x32_bf16 v[60:63], v[136:139], v[194:197], v[60:63]
	v_mfma_f32_16x16x32_bf16 v[60:63], v[124:127], v[190:193], v[60:63]
	v_mfma_f32_16x16x32_bf16 v[44:47], v[124:127], v[204:207], v[44:47]
	v_mfma_f32_16x16x32_bf16 v[44:47], v[136:139], v[208:211], v[44:47]
	v_mfma_f32_16x16x32_bf16 v[48:51], v[120:123], v[208:211], v[48:51]
	v_mfma_f32_16x16x32_bf16 v[48:51], v[116:119], v[204:207], v[48:51]
	v_mfma_f32_16x16x32_bf16 v[32:35], v[116:119], v[212:215], v[32:35]
	v_mfma_f32_16x16x32_bf16 v[32:35], v[120:123], v[216:219], v[32:35]
	v_mfma_f32_16x16x32_bf16 v[28:31], v[136:139], v[216:219], v[28:31]
	v_mfma_f32_16x16x32_bf16 v[28:31], v[124:127], v[212:215], v[28:31]
	v_mfma_f32_16x16x32_bf16 v[12:15], v[124:127], v[228:231], v[12:15]
	v_mfma_f32_16x16x32_bf16 v[12:15], v[136:139], v[232:235], v[12:15]
	v_mfma_f32_16x16x32_bf16 v[16:19], v[120:123], v[232:235], v[16:19]
	v_mfma_f32_16x16x32_bf16 v[16:19], v[116:119], v[228:231], v[16:19]
	v_mfma_f32_16x16x32_bf16 v[56:59], v[148:151], v[190:193], v[56:59]
	v_mfma_f32_16x16x32_bf16 v[56:59], v[152:155], v[194:197], v[56:59]
	v_mfma_f32_16x16x32_bf16 v[52:55], v[186:189], v[194:197], v[52:55]
	v_mfma_f32_16x16x32_bf16 v[52:55], v[182:185], v[190:193], v[52:55]
	v_mfma_f32_16x16x32_bf16 v[36:39], v[182:185], v[204:207], v[36:39]
	v_mfma_f32_16x16x32_bf16 v[36:39], v[186:189], v[208:211], v[36:39]
	v_mfma_f32_16x16x32_bf16 v[40:43], v[152:155], v[208:211], v[40:43]
	v_mfma_f32_16x16x32_bf16 v[40:43], v[148:151], v[204:207], v[40:43]
	v_mfma_f32_16x16x32_bf16 v[24:27], v[148:151], v[212:215], v[24:27]
	v_mfma_f32_16x16x32_bf16 v[24:27], v[152:155], v[216:219], v[24:27]
	v_mfma_f32_16x16x32_bf16 v[20:23], v[186:189], v[216:219], v[20:23]
	v_mfma_f32_16x16x32_bf16 v[20:23], v[182:185], v[212:215], v[20:23]
	v_mfma_f32_16x16x32_bf16 v[4:7], v[182:185], v[228:231], v[4:7]
	v_mfma_f32_16x16x32_bf16 v[4:7], v[186:189], v[232:235], v[4:7]
	v_mfma_f32_16x16x32_bf16 v[8:11], v[152:155], v[232:235], v[8:11]
	v_mfma_f32_16x16x32_bf16 v[8:11], v[148:151], v[228:231], v[8:11]
	s_setprio 0
	s_barrier
	s_add_i32 s68, 0, 0x18000
	s_add_i32 vcc_hi, 0, 0x1c000
	v_add_u32_e32 v136, s68, v200
	v_add_u32_e32 v186, vcc_hi, v200
	ds_read_b128 v[116:119], v136
	ds_read_b128 v[120:123], v136 offset:1024
	ds_read_b128 v[124:127], v136 offset:2048
	ds_read_b128 v[136:139], v136 offset:3072
	ds_read_b128 v[148:151], v186
	ds_read_b128 v[152:155], v186 offset:1024
	ds_read_b128 v[182:185], v186 offset:2048
	ds_read_b128 v[186:189], v186 offset:3072
	s_add_u32 s52, s56, s26
	s_addc_u32 s53, s57, 0
	s_mov_b32 m0, s61
	ds_read_b128 v[190:193], v202 offset:32768
	ds_read_b128 v[194:197], v202 offset:33792
	ds_read_b128 v[204:207], v202 offset:34816
	ds_read_b128 v[208:211], v202 offset:35840
	ds_read_b128 v[212:215], v202 offset:36864
	ds_read_b128 v[216:219], v202 offset:37888
	ds_read_b128 v[228:231], v202 offset:38912
	ds_read_b128 v[232:235], v202 offset:39936
	global_load_lds_dwordx4 v176, s[52:53]
	s_mov_b32 m0, s62
	s_nop 0
	global_load_lds_dwordx4 v172, s[52:53]
	s_waitcnt vmcnt(8)
	s_waitcnt lgkmcnt(0)
	s_barrier
	s_setprio 1
	v_mfma_f32_16x16x32_bf16 v[144:147], v[116:119], v[190:193], v[144:147]
	v_mfma_f32_16x16x32_bf16 v[144:147], v[120:123], v[194:197], v[144:147]
	v_mfma_f32_16x16x32_bf16 v[140:143], v[136:139], v[194:197], v[140:143]
	v_mfma_f32_16x16x32_bf16 v[140:143], v[124:127], v[190:193], v[140:143]
	v_mfma_f32_16x16x32_bf16 v[108:111], v[124:127], v[204:207], v[108:111]
	v_mfma_f32_16x16x32_bf16 v[108:111], v[136:139], v[208:211], v[108:111]
	v_mfma_f32_16x16x32_bf16 v[112:115], v[120:123], v[208:211], v[112:115]
	v_mfma_f32_16x16x32_bf16 v[112:115], v[116:119], v[204:207], v[112:115]
	v_mfma_f32_16x16x32_bf16 v[96:99], v[116:119], v[212:215], v[96:99]
	v_mfma_f32_16x16x32_bf16 v[96:99], v[120:123], v[216:219], v[96:99]
	v_mfma_f32_16x16x32_bf16 v[92:95], v[136:139], v[216:219], v[92:95]
	v_mfma_f32_16x16x32_bf16 v[92:95], v[124:127], v[212:215], v[92:95]
	v_mfma_f32_16x16x32_bf16 v[76:79], v[124:127], v[228:231], v[76:79]
	v_mfma_f32_16x16x32_bf16 v[76:79], v[136:139], v[232:235], v[76:79]
	v_mfma_f32_16x16x32_bf16 v[80:83], v[120:123], v[232:235], v[80:83]
	v_mfma_f32_16x16x32_bf16 v[80:83], v[116:119], v[228:231], v[80:83]
	v_mfma_f32_16x16x32_bf16 v[132:135], v[148:151], v[190:193], v[132:135]
	v_mfma_f32_16x16x32_bf16 v[132:135], v[152:155], v[194:197], v[132:135]
	v_mfma_f32_16x16x32_bf16 v[128:131], v[186:189], v[194:197], v[128:131]
	v_mfma_f32_16x16x32_bf16 v[128:131], v[182:185], v[190:193], v[128:131]
	v_mfma_f32_16x16x32_bf16 v[100:103], v[182:185], v[204:207], v[100:103]
	v_mfma_f32_16x16x32_bf16 v[100:103], v[186:189], v[208:211], v[100:103]
	v_mfma_f32_16x16x32_bf16 v[104:107], v[152:155], v[208:211], v[104:107]
	v_mfma_f32_16x16x32_bf16 v[104:107], v[148:151], v[204:207], v[104:107]
	v_mfma_f32_16x16x32_bf16 v[88:91], v[148:151], v[212:215], v[88:91]
	v_mfma_f32_16x16x32_bf16 v[88:91], v[152:155], v[216:219], v[88:91]
	v_mfma_f32_16x16x32_bf16 v[84:87], v[186:189], v[216:219], v[84:87]
	v_mfma_f32_16x16x32_bf16 v[84:87], v[182:185], v[212:215], v[84:87]
	v_mfma_f32_16x16x32_bf16 v[68:71], v[182:185], v[228:231], v[68:71]
	v_mfma_f32_16x16x32_bf16 v[68:71], v[186:189], v[232:235], v[68:71]
	v_mfma_f32_16x16x32_bf16 v[72:75], v[152:155], v[232:235], v[72:75]
	v_mfma_f32_16x16x32_bf16 v[72:75], v[148:151], v[228:231], v[72:75]
	s_setprio 0
	s_barrier
	s_add_u32 s52, s34, 0x40000
	s_addc_u32 s53, s35, 0
	s_add_i32 s56, s68, s58
	s_mov_b32 m0, s56
	ds_read_b128 v[190:193], v202 offset:49152
	ds_read_b128 v[194:197], v202 offset:50176
	ds_read_b128 v[204:207], v202 offset:51200
	ds_read_b128 v[208:211], v202 offset:52224
	ds_read_b128 v[212:215], v202 offset:53248
	ds_read_b128 v[216:219], v202 offset:54272
	ds_read_b128 v[228:231], v202 offset:55296
	ds_read_b128 v[232:235], v202 offset:56320
	global_load_lds_dwordx4 v174, s[52:53]
	s_add_i32 m0, s56, 0x2000
	s_add_u32 s34, s34, 0x44000
	global_load_lds_dwordx4 v0, s[52:53]
	s_addc_u32 s35, s35, 0
	s_add_i32 s52, vcc_hi, s58
	s_mov_b32 m0, s52
	s_nop 0
	global_load_lds_dwordx4 v174, s[34:35]
	s_add_i32 m0, s52, 0x2000
	s_nop 0
	global_load_lds_dwordx4 v0, s[34:35]
	s_mov_b32 m0, s71
	s_nop 0
	global_load_lds_dwordx4 v176, s[100:101]
	s_mov_b32 m0, s76
	s_nop 0
	global_load_lds_dwordx4 v172, s[100:101]
	s_waitcnt vmcnt(8)
	s_waitcnt lgkmcnt(0)
	s_barrier
	s_setprio 1
	v_mfma_f32_16x16x32_bf16 v[64:67], v[116:119], v[190:193], v[64:67]
	v_mfma_f32_16x16x32_bf16 v[64:67], v[120:123], v[194:197], v[64:67]
	v_mfma_f32_16x16x32_bf16 v[60:63], v[136:139], v[194:197], v[60:63]
	v_mfma_f32_16x16x32_bf16 v[60:63], v[124:127], v[190:193], v[60:63]
	v_mfma_f32_16x16x32_bf16 v[44:47], v[124:127], v[204:207], v[44:47]
	v_mfma_f32_16x16x32_bf16 v[44:47], v[136:139], v[208:211], v[44:47]
	v_mfma_f32_16x16x32_bf16 v[48:51], v[120:123], v[208:211], v[48:51]
	v_mfma_f32_16x16x32_bf16 v[48:51], v[116:119], v[204:207], v[48:51]
	v_mfma_f32_16x16x32_bf16 v[32:35], v[116:119], v[212:215], v[32:35]
	v_mfma_f32_16x16x32_bf16 v[32:35], v[120:123], v[216:219], v[32:35]
	v_mfma_f32_16x16x32_bf16 v[28:31], v[136:139], v[216:219], v[28:31]
	v_mfma_f32_16x16x32_bf16 v[28:31], v[124:127], v[212:215], v[28:31]
	v_mfma_f32_16x16x32_bf16 v[12:15], v[124:127], v[228:231], v[12:15]
	v_mfma_f32_16x16x32_bf16 v[12:15], v[136:139], v[232:235], v[12:15]
	v_mfma_f32_16x16x32_bf16 v[16:19], v[120:123], v[232:235], v[16:19]
	v_mfma_f32_16x16x32_bf16 v[16:19], v[116:119], v[228:231], v[16:19]
	v_mfma_f32_16x16x32_bf16 v[56:59], v[148:151], v[190:193], v[56:59]
	v_mfma_f32_16x16x32_bf16 v[56:59], v[152:155], v[194:197], v[56:59]
	v_mfma_f32_16x16x32_bf16 v[52:55], v[186:189], v[194:197], v[52:55]
	v_mfma_f32_16x16x32_bf16 v[52:55], v[182:185], v[190:193], v[52:55]
	v_mfma_f32_16x16x32_bf16 v[36:39], v[182:185], v[204:207], v[36:39]
	v_mfma_f32_16x16x32_bf16 v[36:39], v[186:189], v[208:211], v[36:39]
	v_mfma_f32_16x16x32_bf16 v[40:43], v[152:155], v[208:211], v[40:43]
	v_mfma_f32_16x16x32_bf16 v[40:43], v[148:151], v[204:207], v[40:43]
	v_mfma_f32_16x16x32_bf16 v[24:27], v[148:151], v[212:215], v[24:27]
	v_mfma_f32_16x16x32_bf16 v[24:27], v[152:155], v[216:219], v[24:27]
	v_mfma_f32_16x16x32_bf16 v[20:23], v[186:189], v[216:219], v[20:23]
	v_mfma_f32_16x16x32_bf16 v[20:23], v[182:185], v[212:215], v[20:23]
	v_mfma_f32_16x16x32_bf16 v[4:7], v[182:185], v[228:231], v[4:7]
	v_mfma_f32_16x16x32_bf16 v[4:7], v[186:189], v[232:235], v[4:7]
	v_mfma_f32_16x16x32_bf16 v[8:11], v[152:155], v[232:235], v[8:11]
	v_mfma_f32_16x16x32_bf16 v[8:11], v[148:151], v[228:231], v[8:11]
	s_setprio 0
	s_barrier
	s_add_u32 s49, s49, 0x80000
	s_addc_u32 s97, s97, 0
	s_add_u32 s42, s42, 0x100
	s_addc_u32 s43, s43, 0
	s_cmp_ge_u32 vcc_lo, s69
	s_mov_b32 s34, vcc_lo
	s_cbranch_scc0 .LBB0_559
	s_and_b64 vcc, exec, s[46:47]
	s_cbranch_vccz .LBB0_562
	s_barrier
